# P7 short conv: hand-written loop, tap weights loaded once per thread, token loop software-pipelined four deep with counted waits (was one load round trip per item)
# speedup vs baseline: 1.0045x; 1.0045x over previous
.LBB0_1019:
	s_or_b64 exec, exec, s[0:1]
	s_waitcnt lgkmcnt(0)
	v_mov_b32_e32 v1, v0
	s_barrier
	s_lshl_b32 s1, s2, 9
	v_readfirstlane_b32 s0, v1
	s_and_b32 s0, s0, 0xffffff00
	s_add_i32 s0, s0, s1
	v_or_b32_sdwa v1, s0, v1 dst_sel:DWORD dst_unused:UNUSED_PAD src0_sel:DWORD src1_sel:BYTE_0
	s_mov_b32 s0, 0x200000
	v_cmp_gt_i32_e32 vcc, s0, v1
	s_and_saveexec_b64 s[0:1], vcc
	s_cbranch_execz .LBB0_1038
	s_lshl_b32 s3, s33, 9
	v_lshlrev_b32_e32 v12, 3, v1
	s_lshl_b32 s14, s33, 12
	s_mov_b64 s[6:7], 0
	s_movk_i32 s15, 0x4000
	v_mov_b32_e32 v13, 0xfff
	v_mov_b32_e32 v14, 0x1fff
	v_mov_b32_e32 v7, 0
	s_mov_b64 s[8:9], 0x1000
	s_movk_i32 s26, 0x1000
	s_mov_b32 s27, 0x1fffff
	v_and_b32_e32 v23, 0x1f8, v12
	v_readlane_b32 s42, v255, 20
	v_readlane_b32 s43, v255, 21
	v_lshlrev_b32_e32 v6, 1, v23
	v_lshlrev_b32_e32 v16, 2, v23
	v_mov_b32_e32 v15, 0x400
	v_add_u32_e32 v17, 0x1000, v16
	s_nop 4
	global_load_dwordx4 v[66:69], v16, s[42:43]
	global_load_dwordx4 v[70:73], v16, s[42:43] offset:16
	global_load_dwordx4 v[74:77], v16, s[42:43] offset:2048
	global_load_dwordx4 v[78:81], v16, s[42:43] offset:2064
	global_load_dwordx4 v[82:85], v17, s[42:43]
	global_load_dwordx4 v[86:89], v17, s[42:43] offset:16
	v_min_i32_e32 v16, s27, v1
	v_mov_b32_e32 v107, v1
	v_ashrrev_i32_e32 v17, 6, v16
	v_cmp_gt_i32_e32 vcc, s15, v17
	v_lshl_or_b32 v106, v17, 10, v6
	v_add_u32_e32 v1, s3, v1
	v_cndmask_b32_e32 v18, v13, v14, vcc
	v_and_b32_e32 v19, v18, v17
	v_cmp_ne_u32_e32 vcc, 0, v19
	global_load_dwordx4 v[94:97], v106, s[10:11]
	global_load_dwordx4 v[102:105], v106, s[28:29]
	v_cndmask_b32_e32 v20, 0, v15, vcc
	v_cmp_ne_u32_e32 vcc, v19, v18
	v_sub_u32_e32 v20, v106, v20
	s_nop 0
	v_cndmask_b32_e32 v21, 0, v15, vcc
	v_add_u32_e32 v21, v106, v21
	global_load_dwordx4 v[90:93], v20, s[10:11]
	global_load_dwordx4 v[98:101], v21, s[10:11]
	v_min_i32_e32 v16, s27, v1
	v_mov_b32_e32 v127, v1
	v_ashrrev_i32_e32 v17, 6, v16
	v_cmp_gt_i32_e32 vcc, s15, v17
	v_lshl_or_b32 v126, v17, 10, v6
	v_add_u32_e32 v1, s3, v1
	v_cndmask_b32_e32 v18, v13, v14, vcc
	v_and_b32_e32 v19, v18, v17
	v_cmp_ne_u32_e32 vcc, 0, v19
	global_load_dwordx4 v[114:117], v126, s[10:11]
	global_load_dwordx4 v[122:125], v126, s[28:29]
	v_cndmask_b32_e32 v20, 0, v15, vcc
	v_cmp_ne_u32_e32 vcc, v19, v18
	v_sub_u32_e32 v20, v126, v20
	s_nop 0
	v_cndmask_b32_e32 v21, 0, v15, vcc
	v_add_u32_e32 v21, v126, v21
	global_load_dwordx4 v[110:113], v20, s[10:11]
	global_load_dwordx4 v[118:121], v21, s[10:11]
	v_min_i32_e32 v16, s27, v1
	v_mov_b32_e32 v147, v1
	v_ashrrev_i32_e32 v17, 6, v16
	v_cmp_gt_i32_e32 vcc, s15, v17
	v_lshl_or_b32 v146, v17, 10, v6
	v_add_u32_e32 v1, s3, v1
	v_cndmask_b32_e32 v18, v13, v14, vcc
	v_and_b32_e32 v19, v18, v17
	v_cmp_ne_u32_e32 vcc, 0, v19
	global_load_dwordx4 v[134:137], v146, s[10:11]
	global_load_dwordx4 v[142:145], v146, s[28:29]
	v_cndmask_b32_e32 v20, 0, v15, vcc
	v_cmp_ne_u32_e32 vcc, v19, v18
	v_sub_u32_e32 v20, v146, v20
	s_nop 0
	v_cndmask_b32_e32 v21, 0, v15, vcc
	v_add_u32_e32 v21, v146, v21
	global_load_dwordx4 v[130:133], v20, s[10:11]
	global_load_dwordx4 v[138:141], v21, s[10:11]
.Lp7_step0:
	v_cmp_ge_i32_e64 s[44:45], s27, v107
	v_min_i32_e32 v16, s27, v1
	v_mov_b32_e32 v167, v1
	v_ashrrev_i32_e32 v17, 6, v16
	v_cmp_gt_i32_e32 vcc, s15, v17
	v_lshl_or_b32 v166, v17, 10, v6
	v_add_u32_e32 v1, s3, v1
	v_cndmask_b32_e32 v18, v13, v14, vcc
	v_and_b32_e32 v19, v18, v17
	v_cmp_ne_u32_e32 vcc, 0, v19
	global_load_dwordx4 v[154:157], v166, s[10:11]
	global_load_dwordx4 v[162:165], v166, s[28:29]
	v_cndmask_b32_e32 v20, 0, v15, vcc
	v_cmp_ne_u32_e32 vcc, v19, v18
	v_sub_u32_e32 v20, v166, v20
	s_nop 0
	v_cndmask_b32_e32 v21, 0, v15, vcc
	v_add_u32_e32 v21, v166, v21
	global_load_dwordx4 v[150:153], v20, s[10:11]
	global_load_dwordx4 v[158:161], v21, s[10:11]
	s_cmp_eq_u64 s[44:45], 0
	s_cbranch_scc1 .LBB0_1038
	s_waitcnt vmcnt(12)
	v_lshrrev_b32_e32 v22, 10, v106
	v_cmp_gt_i32_e32 vcc, s15, v22
	v_lshlrev_b32_e32 v26, 16, v94
	v_and_b32_e32 v27, 0xffff0000, v94
	v_lshlrev_b32_e32 v28, 16, v95
	v_and_b32_e32 v29, 0xffff0000, v95
	v_lshlrev_b32_e32 v30, 16, v96
	v_and_b32_e32 v31, 0xffff0000, v96
	v_lshlrev_b32_e32 v32, 16, v97
	v_and_b32_e32 v33, 0xffff0000, v97
	v_cndmask_b32_e32 v23, v13, v14, vcc
	v_and_b32_e32 v24, v23, v22
	v_cmp_ne_u32_e64 s[46:47], 0, v24
	v_cmp_ne_u32_e64 s[48:49], v24, v23
	v_lshlrev_b32_e32 v50, 16, v102
	v_and_b32_e32 v51, 0xffff0000, v102
	v_lshlrev_b32_e32 v52, 16, v103
	v_and_b32_e32 v53, 0xffff0000, v103
	v_lshlrev_b32_e32 v54, 16, v104
	v_and_b32_e32 v55, 0xffff0000, v104
	v_lshlrev_b32_e32 v56, 16, v105
	v_and_b32_e32 v57, 0xffff0000, v105
	v_cndmask_b32_e64 v90, 0, v90, s[46:47]
	v_cndmask_b32_e64 v91, 0, v91, s[46:47]
	v_cndmask_b32_e64 v92, 0, v92, s[46:47]
	v_cndmask_b32_e64 v93, 0, v93, s[46:47]
	v_cndmask_b32_e64 v98, 0, v98, s[48:49]
	v_cndmask_b32_e64 v99, 0, v99, s[48:49]
	v_cndmask_b32_e64 v100, 0, v100, s[48:49]
	v_cndmask_b32_e64 v101, 0, v101, s[48:49]
	v_lshlrev_b32_e32 v34, 16, v90
	v_and_b32_e32 v35, 0xffff0000, v90
	v_lshlrev_b32_e32 v36, 16, v91
	v_and_b32_e32 v37, 0xffff0000, v91
	v_lshlrev_b32_e32 v38, 16, v92
	v_and_b32_e32 v39, 0xffff0000, v92
	v_lshlrev_b32_e32 v40, 16, v93
	v_and_b32_e32 v41, 0xffff0000, v93
	v_lshlrev_b32_e32 v42, 16, v98
	v_and_b32_e32 v43, 0xffff0000, v98
	v_lshlrev_b32_e32 v44, 16, v99
	v_and_b32_e32 v45, 0xffff0000, v99
	v_lshlrev_b32_e32 v46, 16, v100
	v_and_b32_e32 v47, 0xffff0000, v100
	v_lshlrev_b32_e32 v48, 16, v101
	v_and_b32_e32 v49, 0xffff0000, v101
	v_pk_mul_f32 v[58:59], v[74:75], v[26:27]
	v_pk_mul_f32 v[60:61], v[76:77], v[28:29]
	v_pk_mul_f32 v[62:63], v[78:79], v[30:31]
	v_pk_mul_f32 v[64:65], v[80:81], v[32:33]
	v_pk_fma_f32 v[58:59], v[66:67], v[34:35], v[58:59]
	v_pk_fma_f32 v[60:61], v[68:69], v[36:37], v[60:61]
	v_pk_fma_f32 v[62:63], v[70:71], v[38:39], v[62:63]
	v_pk_fma_f32 v[64:65], v[72:73], v[40:41], v[64:65]
	v_pk_fma_f32 v[58:59], v[82:83], v[42:43], v[58:59]
	v_pk_fma_f32 v[60:61], v[84:85], v[44:45], v[60:61]
	v_pk_fma_f32 v[62:63], v[86:87], v[46:47], v[62:63]
	v_pk_fma_f32 v[64:65], v[88:89], v[48:49], v[64:65]
	v_pk_mul_f32 v[58:59], v[58:59], v[50:51]
	v_pk_mul_f32 v[60:61], v[60:61], v[52:53]
	v_pk_mul_f32 v[62:63], v[62:63], v[54:55]
	v_pk_mul_f32 v[64:65], v[64:65], v[56:57]
	v_cvt_pk_bf16_f32 v94, v58, v59
	v_cvt_pk_bf16_f32 v95, v60, v61
	v_cvt_pk_bf16_f32 v96, v62, v63
	v_cvt_pk_bf16_f32 v97, v64, v65
	s_and_saveexec_b64 s[12:13], s[44:45]
	global_store_dwordx4 v106, v[94:97], s[28:29]
	s_mov_b64 exec, s[12:13]
.Lp7_step1:
	v_cmp_ge_i32_e64 s[44:45], s27, v127
	v_min_i32_e32 v16, s27, v1
	v_mov_b32_e32 v107, v1
	v_ashrrev_i32_e32 v17, 6, v16
	v_cmp_gt_i32_e32 vcc, s15, v17
	v_lshl_or_b32 v106, v17, 10, v6
	v_add_u32_e32 v1, s3, v1
	v_cndmask_b32_e32 v18, v13, v14, vcc
	v_and_b32_e32 v19, v18, v17
	v_cmp_ne_u32_e32 vcc, 0, v19
	global_load_dwordx4 v[94:97], v106, s[10:11]
	global_load_dwordx4 v[102:105], v106, s[28:29]
	v_cndmask_b32_e32 v20, 0, v15, vcc
	v_cmp_ne_u32_e32 vcc, v19, v18
	v_sub_u32_e32 v20, v106, v20
	s_nop 0
	v_cndmask_b32_e32 v21, 0, v15, vcc
	v_add_u32_e32 v21, v106, v21
	global_load_dwordx4 v[90:93], v20, s[10:11]
	global_load_dwordx4 v[98:101], v21, s[10:11]
	s_cmp_eq_u64 s[44:45], 0
	s_cbranch_scc1 .LBB0_1038
	s_waitcnt vmcnt(12)
	v_lshrrev_b32_e32 v22, 10, v126
	v_cmp_gt_i32_e32 vcc, s15, v22
	v_lshlrev_b32_e32 v26, 16, v114
	v_and_b32_e32 v27, 0xffff0000, v114
	v_lshlrev_b32_e32 v28, 16, v115
	v_and_b32_e32 v29, 0xffff0000, v115
	v_lshlrev_b32_e32 v30, 16, v116
	v_and_b32_e32 v31, 0xffff0000, v116
	v_lshlrev_b32_e32 v32, 16, v117
	v_and_b32_e32 v33, 0xffff0000, v117
	v_cndmask_b32_e32 v23, v13, v14, vcc
	v_and_b32_e32 v24, v23, v22
	v_cmp_ne_u32_e64 s[46:47], 0, v24
	v_cmp_ne_u32_e64 s[48:49], v24, v23
	v_lshlrev_b32_e32 v50, 16, v122
	v_and_b32_e32 v51, 0xffff0000, v122
	v_lshlrev_b32_e32 v52, 16, v123
	v_and_b32_e32 v53, 0xffff0000, v123
	v_lshlrev_b32_e32 v54, 16, v124
	v_and_b32_e32 v55, 0xffff0000, v124
	v_lshlrev_b32_e32 v56, 16, v125
	v_and_b32_e32 v57, 0xffff0000, v125
	v_cndmask_b32_e64 v110, 0, v110, s[46:47]
	v_cndmask_b32_e64 v111, 0, v111, s[46:47]
	v_cndmask_b32_e64 v112, 0, v112, s[46:47]
	v_cndmask_b32_e64 v113, 0, v113, s[46:47]
	v_cndmask_b32_e64 v118, 0, v118, s[48:49]
	v_cndmask_b32_e64 v119, 0, v119, s[48:49]
	v_cndmask_b32_e64 v120, 0, v120, s[48:49]
	v_cndmask_b32_e64 v121, 0, v121, s[48:49]
	v_lshlrev_b32_e32 v34, 16, v110
	v_and_b32_e32 v35, 0xffff0000, v110
	v_lshlrev_b32_e32 v36, 16, v111
	v_and_b32_e32 v37, 0xffff0000, v111
	v_lshlrev_b32_e32 v38, 16, v112
	v_and_b32_e32 v39, 0xffff0000, v112
	v_lshlrev_b32_e32 v40, 16, v113
	v_and_b32_e32 v41, 0xffff0000, v113
	v_lshlrev_b32_e32 v42, 16, v118
	v_and_b32_e32 v43, 0xffff0000, v118
	v_lshlrev_b32_e32 v44, 16, v119
	v_and_b32_e32 v45, 0xffff0000, v119
	v_lshlrev_b32_e32 v46, 16, v120
	v_and_b32_e32 v47, 0xffff0000, v120
	v_lshlrev_b32_e32 v48, 16, v121
	v_and_b32_e32 v49, 0xffff0000, v121
	v_pk_mul_f32 v[58:59], v[74:75], v[26:27]
	v_pk_mul_f32 v[60:61], v[76:77], v[28:29]
	v_pk_mul_f32 v[62:63], v[78:79], v[30:31]
	v_pk_mul_f32 v[64:65], v[80:81], v[32:33]
	v_pk_fma_f32 v[58:59], v[66:67], v[34:35], v[58:59]
	v_pk_fma_f32 v[60:61], v[68:69], v[36:37], v[60:61]
	v_pk_fma_f32 v[62:63], v[70:71], v[38:39], v[62:63]
	v_pk_fma_f32 v[64:65], v[72:73], v[40:41], v[64:65]
	v_pk_fma_f32 v[58:59], v[82:83], v[42:43], v[58:59]
	v_pk_fma_f32 v[60:61], v[84:85], v[44:45], v[60:61]
	v_pk_fma_f32 v[62:63], v[86:87], v[46:47], v[62:63]
	v_pk_fma_f32 v[64:65], v[88:89], v[48:49], v[64:65]
	v_pk_mul_f32 v[58:59], v[58:59], v[50:51]
	v_pk_mul_f32 v[60:61], v[60:61], v[52:53]
	v_pk_mul_f32 v[62:63], v[62:63], v[54:55]
	v_pk_mul_f32 v[64:65], v[64:65], v[56:57]
	v_cvt_pk_bf16_f32 v114, v58, v59
	v_cvt_pk_bf16_f32 v115, v60, v61
	v_cvt_pk_bf16_f32 v116, v62, v63
	v_cvt_pk_bf16_f32 v117, v64, v65
	s_and_saveexec_b64 s[12:13], s[44:45]
	global_store_dwordx4 v126, v[114:117], s[28:29]
	s_mov_b64 exec, s[12:13]
.Lp7_step2:
	v_cmp_ge_i32_e64 s[44:45], s27, v147
	v_min_i32_e32 v16, s27, v1
	v_mov_b32_e32 v127, v1
	v_ashrrev_i32_e32 v17, 6, v16
	v_cmp_gt_i32_e32 vcc, s15, v17
	v_lshl_or_b32 v126, v17, 10, v6
	v_add_u32_e32 v1, s3, v1
	v_cndmask_b32_e32 v18, v13, v14, vcc
	v_and_b32_e32 v19, v18, v17
	v_cmp_ne_u32_e32 vcc, 0, v19
	global_load_dwordx4 v[114:117], v126, s[10:11]
	global_load_dwordx4 v[122:125], v126, s[28:29]
	v_cndmask_b32_e32 v20, 0, v15, vcc
	v_cmp_ne_u32_e32 vcc, v19, v18
	v_sub_u32_e32 v20, v126, v20
	s_nop 0
	v_cndmask_b32_e32 v21, 0, v15, vcc
	v_add_u32_e32 v21, v126, v21
	global_load_dwordx4 v[110:113], v20, s[10:11]
	global_load_dwordx4 v[118:121], v21, s[10:11]
	s_cmp_eq_u64 s[44:45], 0
	s_cbranch_scc1 .LBB0_1038
	s_waitcnt vmcnt(12)
	v_lshrrev_b32_e32 v22, 10, v146
	v_cmp_gt_i32_e32 vcc, s15, v22
	v_lshlrev_b32_e32 v26, 16, v134
	v_and_b32_e32 v27, 0xffff0000, v134
	v_lshlrev_b32_e32 v28, 16, v135
	v_and_b32_e32 v29, 0xffff0000, v135
	v_lshlrev_b32_e32 v30, 16, v136
	v_and_b32_e32 v31, 0xffff0000, v136
	v_lshlrev_b32_e32 v32, 16, v137
	v_and_b32_e32 v33, 0xffff0000, v137
	v_cndmask_b32_e32 v23, v13, v14, vcc
	v_and_b32_e32 v24, v23, v22
	v_cmp_ne_u32_e64 s[46:47], 0, v24
	v_cmp_ne_u32_e64 s[48:49], v24, v23
	v_lshlrev_b32_e32 v50, 16, v142
	v_and_b32_e32 v51, 0xffff0000, v142
	v_lshlrev_b32_e32 v52, 16, v143
	v_and_b32_e32 v53, 0xffff0000, v143
	v_lshlrev_b32_e32 v54, 16, v144
	v_and_b32_e32 v55, 0xffff0000, v144
	v_lshlrev_b32_e32 v56, 16, v145
	v_and_b32_e32 v57, 0xffff0000, v145
	v_cndmask_b32_e64 v130, 0, v130, s[46:47]
	v_cndmask_b32_e64 v131, 0, v131, s[46:47]
	v_cndmask_b32_e64 v132, 0, v132, s[46:47]
	v_cndmask_b32_e64 v133, 0, v133, s[46:47]
	v_cndmask_b32_e64 v138, 0, v138, s[48:49]
	v_cndmask_b32_e64 v139, 0, v139, s[48:49]
	v_cndmask_b32_e64 v140, 0, v140, s[48:49]
	v_cndmask_b32_e64 v141, 0, v141, s[48:49]
	v_lshlrev_b32_e32 v34, 16, v130
	v_and_b32_e32 v35, 0xffff0000, v130
	v_lshlrev_b32_e32 v36, 16, v131
	v_and_b32_e32 v37, 0xffff0000, v131
	v_lshlrev_b32_e32 v38, 16, v132
	v_and_b32_e32 v39, 0xffff0000, v132
	v_lshlrev_b32_e32 v40, 16, v133
	v_and_b32_e32 v41, 0xffff0000, v133
	v_lshlrev_b32_e32 v42, 16, v138
	v_and_b32_e32 v43, 0xffff0000, v138
	v_lshlrev_b32_e32 v44, 16, v139
	v_and_b32_e32 v45, 0xffff0000, v139
	v_lshlrev_b32_e32 v46, 16, v140
	v_and_b32_e32 v47, 0xffff0000, v140
	v_lshlrev_b32_e32 v48, 16, v141
	v_and_b32_e32 v49, 0xffff0000, v141
	v_pk_mul_f32 v[58:59], v[74:75], v[26:27]
	v_pk_mul_f32 v[60:61], v[76:77], v[28:29]
	v_pk_mul_f32 v[62:63], v[78:79], v[30:31]
	v_pk_mul_f32 v[64:65], v[80:81], v[32:33]
	v_pk_fma_f32 v[58:59], v[66:67], v[34:35], v[58:59]
	v_pk_fma_f32 v[60:61], v[68:69], v[36:37], v[60:61]
	v_pk_fma_f32 v[62:63], v[70:71], v[38:39], v[62:63]
	v_pk_fma_f32 v[64:65], v[72:73], v[40:41], v[64:65]
	v_pk_fma_f32 v[58:59], v[82:83], v[42:43], v[58:59]
	v_pk_fma_f32 v[60:61], v[84:85], v[44:45], v[60:61]
	v_pk_fma_f32 v[62:63], v[86:87], v[46:47], v[62:63]
	v_pk_fma_f32 v[64:65], v[88:89], v[48:49], v[64:65]
	v_pk_mul_f32 v[58:59], v[58:59], v[50:51]
	v_pk_mul_f32 v[60:61], v[60:61], v[52:53]
	v_pk_mul_f32 v[62:63], v[62:63], v[54:55]
	v_pk_mul_f32 v[64:65], v[64:65], v[56:57]
	v_cvt_pk_bf16_f32 v134, v58, v59
	v_cvt_pk_bf16_f32 v135, v60, v61
	v_cvt_pk_bf16_f32 v136, v62, v63
	v_cvt_pk_bf16_f32 v137, v64, v65
	s_and_saveexec_b64 s[12:13], s[44:45]
	global_store_dwordx4 v146, v[134:137], s[28:29]
	s_mov_b64 exec, s[12:13]
.Lp7_step3:
	v_cmp_ge_i32_e64 s[44:45], s27, v167
	v_min_i32_e32 v16, s27, v1
	v_mov_b32_e32 v147, v1
	v_ashrrev_i32_e32 v17, 6, v16
	v_cmp_gt_i32_e32 vcc, s15, v17
	v_lshl_or_b32 v146, v17, 10, v6
	v_add_u32_e32 v1, s3, v1
	v_cndmask_b32_e32 v18, v13, v14, vcc
	v_and_b32_e32 v19, v18, v17
	v_cmp_ne_u32_e32 vcc, 0, v19
	global_load_dwordx4 v[134:137], v146, s[10:11]
	global_load_dwordx4 v[142:145], v146, s[28:29]
	v_cndmask_b32_e32 v20, 0, v15, vcc
	v_cmp_ne_u32_e32 vcc, v19, v18
	v_sub_u32_e32 v20, v146, v20
	s_nop 0
	v_cndmask_b32_e32 v21, 0, v15, vcc
	v_add_u32_e32 v21, v146, v21
	global_load_dwordx4 v[130:133], v20, s[10:11]
	global_load_dwordx4 v[138:141], v21, s[10:11]
	s_cmp_eq_u64 s[44:45], 0
	s_cbranch_scc1 .LBB0_1038
	s_waitcnt vmcnt(12)
	v_lshrrev_b32_e32 v22, 10, v166
	v_cmp_gt_i32_e32 vcc, s15, v22
	v_lshlrev_b32_e32 v26, 16, v154
	v_and_b32_e32 v27, 0xffff0000, v154
	v_lshlrev_b32_e32 v28, 16, v155
	v_and_b32_e32 v29, 0xffff0000, v155
	v_lshlrev_b32_e32 v30, 16, v156
	v_and_b32_e32 v31, 0xffff0000, v156
	v_lshlrev_b32_e32 v32, 16, v157
	v_and_b32_e32 v33, 0xffff0000, v157
	v_cndmask_b32_e32 v23, v13, v14, vcc
	v_and_b32_e32 v24, v23, v22
	v_cmp_ne_u32_e64 s[46:47], 0, v24
	v_cmp_ne_u32_e64 s[48:49], v24, v23
	v_lshlrev_b32_e32 v50, 16, v162
	v_and_b32_e32 v51, 0xffff0000, v162
	v_lshlrev_b32_e32 v52, 16, v163
	v_and_b32_e32 v53, 0xffff0000, v163
	v_lshlrev_b32_e32 v54, 16, v164
	v_and_b32_e32 v55, 0xffff0000, v164
	v_lshlrev_b32_e32 v56, 16, v165
	v_and_b32_e32 v57, 0xffff0000, v165
	v_cndmask_b32_e64 v150, 0, v150, s[46:47]
	v_cndmask_b32_e64 v151, 0, v151, s[46:47]
	v_cndmask_b32_e64 v152, 0, v152, s[46:47]
	v_cndmask_b32_e64 v153, 0, v153, s[46:47]
	v_cndmask_b32_e64 v158, 0, v158, s[48:49]
	v_cndmask_b32_e64 v159, 0, v159, s[48:49]
	v_cndmask_b32_e64 v160, 0, v160, s[48:49]
	v_cndmask_b32_e64 v161, 0, v161, s[48:49]
	v_lshlrev_b32_e32 v34, 16, v150
	v_and_b32_e32 v35, 0xffff0000, v150
	v_lshlrev_b32_e32 v36, 16, v151
	v_and_b32_e32 v37, 0xffff0000, v151
	v_lshlrev_b32_e32 v38, 16, v152
	v_and_b32_e32 v39, 0xffff0000, v152
	v_lshlrev_b32_e32 v40, 16, v153
	v_and_b32_e32 v41, 0xffff0000, v153
	v_lshlrev_b32_e32 v42, 16, v158
	v_and_b32_e32 v43, 0xffff0000, v158
	v_lshlrev_b32_e32 v44, 16, v159
	v_and_b32_e32 v45, 0xffff0000, v159
	v_lshlrev_b32_e32 v46, 16, v160
	v_and_b32_e32 v47, 0xffff0000, v160
	v_lshlrev_b32_e32 v48, 16, v161
	v_and_b32_e32 v49, 0xffff0000, v161
	v_pk_mul_f32 v[58:59], v[74:75], v[26:27]
	v_pk_mul_f32 v[60:61], v[76:77], v[28:29]
	v_pk_mul_f32 v[62:63], v[78:79], v[30:31]
	v_pk_mul_f32 v[64:65], v[80:81], v[32:33]
	v_pk_fma_f32 v[58:59], v[66:67], v[34:35], v[58:59]
	v_pk_fma_f32 v[60:61], v[68:69], v[36:37], v[60:61]
	v_pk_fma_f32 v[62:63], v[70:71], v[38:39], v[62:63]
	v_pk_fma_f32 v[64:65], v[72:73], v[40:41], v[64:65]
	v_pk_fma_f32 v[58:59], v[82:83], v[42:43], v[58:59]
	v_pk_fma_f32 v[60:61], v[84:85], v[44:45], v[60:61]
	v_pk_fma_f32 v[62:63], v[86:87], v[46:47], v[62:63]
	v_pk_fma_f32 v[64:65], v[88:89], v[48:49], v[64:65]
	v_pk_mul_f32 v[58:59], v[58:59], v[50:51]
	v_pk_mul_f32 v[60:61], v[60:61], v[52:53]
	v_pk_mul_f32 v[62:63], v[62:63], v[54:55]
	v_pk_mul_f32 v[64:65], v[64:65], v[56:57]
	v_cvt_pk_bf16_f32 v154, v58, v59
	v_cvt_pk_bf16_f32 v155, v60, v61
	v_cvt_pk_bf16_f32 v156, v62, v63
	v_cvt_pk_bf16_f32 v157, v64, v65
	s_and_saveexec_b64 s[12:13], s[44:45]
	global_store_dwordx4 v166, v[154:157], s[28:29]
	s_mov_b64 exec, s[12:13]
	s_branch .Lp7_step0
